# attention phase: static issue priority 1 for the map-1 (younger) waves of each SIMD pair, reset at the end of the phase
# baseline (speedup 1.0000x reference)
; __global__ void __launch_bounds__(NWAVES * 64, 2) hymba_fwd(Args args) {
;     ...
;         __syncthreads();
;         const float lam = ((const float*)ctl)[CW_LAM];
;         constexpr int NU = 512 + 1024;
;         for (;;) {
;             if (tid == 0) MISC[0] = atomicAdd(ctl + CW_QCTR, 1u);
;             __syncthreads();
;             const int u = (int)MISC[0];
.LBB0_290:
	v_mov_b32_e32 v177, 0
	s_barrier
	v_readfirstlane_b32 s98, v210
	s_cmpk_lt_u32 s98, 0x100
	s_cbranch_scc1 .Lattn_prio0
	s_setprio 1
.Lattn_prio0:
	global_load_dword v183, v177, s[70:71] offset:256
	v_mbcnt_hi_u32_b32 v211, -1, v124
	s_add_i32 s15, 0, 0x20000
	s_mov_b32 s48, 2.0
	s_mov_b32 s50, 0x41000000
	s_mov_b32 s58, 0x41200000
	s_mov_b32 s64, 0x41800000
	s_mov_b32 s80, 0x41900000
	s_mov_b32 s82, 0x41c00000
	s_mov_b32 s86, -2.0
	s_mov_b32 s88, 0xc1000000
	s_mov_b32 s90, 0xc1200000
	s_mov_b32 s92, 0xc1800000
	s_mov_b32 s94, 0xc1900000
	s_mov_b32 s96, 0xc1c00000
	s_mov_b32 s4, 0xc1d00000
	s_waitcnt vmcnt(3)
	v_and_b32_e32 v0, 64, v211
	s_mov_b32 s11, 0
	v_mov_b32_e32 v219, s15
	s_mov_b32 s26, 0xf800000
	v_mov_b32_e32 v220, 0x260
	s_movk_i32 s27, 0xd00
	s_movk_i32 s28, 0x100
	s_add_i32 s29, 0, 0x10010
	s_mov_b32 s14, 0x41d00000
	s_mov_b32 s49, 0x40400000
	s_mov_b32 s51, 0x41100000
	s_mov_b32 s59, 0x41300000
	s_mov_b32 s65, 0x41880000
	s_mov_b32 s81, 0x41980000
	s_mov_b32 s83, 0x41c80000
	s_mov_b32 s84, 0xc2000000
	s_mov_b32 s87, 0xc0400000
	s_mov_b32 s89, 0xc1100000
	s_mov_b32 s91, 0xc1300000
	s_mov_b32 s93, 0xc1880000
	s_mov_b32 s95, 0xc1980000
	s_mov_b32 s97, 0xc1c80000
	s_mov_b32 s5, 0xc1d80000
	v_mov_b32_e32 v221, 0x358637bd
	s_movk_i32 s30, 0x7fff
	v_mov_b32_e32 v223, 0x3c800000
	v_xor_b32_e32 v214, 32, v211
	v_add_u32_e32 v213, 64, v0
	v_xor_b32_e32 v252, 1, v211
	v_xor_b32_e32 v253, 2, v211
	v_xor_b32_e32 v254, 4, v211
	v_xor_b32_e32 v212, 8, v211
	v_xor_b32_e32 v218, 16, v211
	v_mov_b32_e32 v178, 0x41d00000
	s_and_saveexec_b64 s[98:99], s[22:23]
	s_cbranch_execz .Lattn_q0
	v_mov_b32_e32 v175, 1
	global_atomic_add v175, v177, v175, s[70:71] sc0

; __device__ __forceinline__ void xcd_barrier(const XcdBarrier& b) {
;     asm volatile("s_waitcnt vmcnt(0)" ::: "memory");
;     __syncthreads();
;     if (threadIdx.x == 0) {
;         unsigned* bar = b.bar;
;         __builtin_amdgcn_s_waitcnt(0);
;         unsigned nloc = b.st[0], nx = b.st[1];
;         if (nloc == 0u) { xcd_barrier_complete(bar, b.x, nloc, nx); b.st[0] = nloc; b.st[1] = nx; }
.LBB0_348:
	s_setprio 0
	s_waitcnt vmcnt(0)
	s_barrier
	s_and_saveexec_b64 s[0:1], s[22:23]
	s_cbranch_execz .LBB0_400
	s_add_i32 s3, 0, 0x20020
	v_mov_b32_e32 v0, s3
	s_waitcnt vmcnt(0) expcnt(0) lgkmcnt(0)
	ds_read_b32 v2, v0
	s_add_i32 s3, 0, 0x20024
	v_mov_b32_e32 v0, s3
	ds_read_b32 v0, v0
	s_waitcnt lgkmcnt(1)
	v_cmp_ne_u32_e32 vcc, 0, v2
	s_cbranch_vccnz .LBB0_364
	s_add_u32 s4, s70, 0x1200
	s_addc_u32 s5, s71, 0
	s_add_u32 s6, s70, 0x1400
	s_addc_u32 s7, s71, 0
	s_add_u32 s8, s70, 0x1500
	s_addc_u32 s9, s71, 0
	s_add_u32 s10, s70, 0x1600
	s_addc_u32 s11, s71, 0
	s_add_u32 s14, s70, 0x1700
	s_addc_u32 s15, s71, 0
	s_add_u32 s24, s70, 0x1800
	s_addc_u32 s25, s71, 0
	s_add_u32 s26, s70, 0x1900
	s_addc_u32 s27, s71, 0
	s_add_u32 s28, s70, 0x1a00
	s_addc_u32 s29, s71, 0
	s_add_u32 s30, s70, 0x1b00
	s_addc_u32 s31, s71, 0
	s_add_u32 s48, s70, 0x1c00
	s_addc_u32 s49, s71, 0
	s_add_u32 s50, s70, 0x1d00
	s_addc_u32 s51, s71, 0
	s_add_u32 s58, s70, 0x1e00
	s_addc_u32 s59, s71, 0
	s_add_u32 s64, s70, 0x1f00
	s_addc_u32 s65, s71, 0
	s_add_u32 s80, s70, 0x2000
	s_addc_u32 s81, s71, 0
	s_add_u32 s82, s70, 0x2100
	s_addc_u32 s83, s71, 0
	s_add_u32 s84, s70, 0x2200
	v_readlane_b32 s3, v255, 8
	s_addc_u32 s85, s71, 0
	s_mul_i32 s3, s75, s3
	s_add_u32 s86, s70, 0x2300
	s_mul_i32 s3, s3, s74
	s_addc_u32 s87, s71, 0
	s_mov_b32 s33, 1
	v_mov_b32_e32 v16, 0
	s_branch .LBB0_352
